# ProjGate V^T tiles: 8 two-byte scatter stores per accumulator block replaced by an LDS round trip (ds_write_b128 + 2 ds_read_b64_tr_b16 in the idle As[1][1] slot) and one 16-byte store per lane
# speedup vs baseline: 1.0098x; 1.0018x over previous
; __device__ __forceinline__ float rstd_of(const float* ssq, int row) {
;     const f32x4* q = (const f32x4*)(ssq + (size_t)row * 16); const f32x4 a = q[0], b = q[1], c = q[2], d = q[3];
;     const float t = (((a.x + a.y) + (a.z + a.w)) + ((b.x + b.y) + (b.z + b.w))) + (((c.x + c.y) + (c.z + c.w)) + ((d.x + d.y) + (d.z + d.w)));
;     return 1.0f / sqrtf(t * (1.0f / DM) + 1e-6f); }
;     __device__ __forceinline__ void operator()(const pg8::f32x4 (&acc)[2][2][4][2], const pg8::Unit& u, int wr, int wc, int fr, int fq) const {
;     ...
;                         if (vt_all || (vt_half && bj == 1)) {
;                             bf16_t* vp = vt + (size_t)(vrow0 + bj * 128) * S + row;
;                             vp[0 * (size_t)S] = (bf16_t)(w.x & 0xffffu); vp[1 * (size_t)S] = (bf16_t)(w.x >> 16); vp[2 * (size_t)S] = (bf16_t)(w.y & 0xffffu); vp[3 * (size_t)S] = (bf16_t)(w.y >> 16);
.LBB0_345:
	v_lshl_add_u32 v158, s44, 8, v35
	v_lshrrev_b32_e32 v220, 2, v158
	v_lshrrev_b32_e32 v221, 3, v158
	v_xor_b32_e32 v220, v220, v221
	v_and_b32_e32 v220, 1, v220
	v_mul_u32_u24_e32 v220, 12, v220
	v_xor_b32_e32 v220, v158, v220
	v_mov_b32_e32 v221, 0
	v_and_b32_e32 v250, -16, v220
	v_and_b32_e32 v251, 8, v35
	v_or_b32_e32 v250, v250, v251
	v_mov_b32_e32 v251, 0
	v_and_b32_e32 v248, 7, v35
	v_lshlrev_b32_e32 v248, 15, v248
	v_mov_b32_e32 v249, 0
	v_mbcnt_lo_u32_b32 v226, -1, 0
	v_mbcnt_hi_u32_b32 v226, -1, v226
	v_and_b32_e32 v227, 48, v226
	v_bfe_u32 v232, v226, 2, 2
	v_add_u32_e32 v227, v227, v232
	v_bfe_u32 v232, v226, 1, 1
	v_lshl_add_u32 v227, v232, 2, v227
	v_lshlrev_b32_e32 v227, 4, v227
	v_and_b32_e32 v232, 1, v226
	v_lshl_add_u32 v227, v232, 3, v227
	s_add_i32 s100, s50, 0xc000
	v_add_u32_e32 v227, s100, v227
	v_lshl_add_u32 v226, v226, 4, s100
	v_readfirstlane_b32 s100, v241
	s_cmp_eq_u32 s100, s44
	s_cbranch_scc1 .Lrstd_have_pg
	v_mbcnt_lo_u32_b32 v210, -1, 0
	v_mbcnt_hi_u32_b32 v210, -1, v210
	v_lshrrev_b32_e32 v211, 4, v210
	v_and_b32_e32 v212, 1, v211
	v_lshrrev_b32_e32 v211, 1, v211
	v_lshlrev_b32_e32 v212, 5, v212
	v_lshl_add_u32 v212, v211, 7, v212
	v_add_u32_e32 v212, v212, v158
	v_mov_b32_e32 v213, 0
	v_lshlrev_b64 v[212:213], 6, v[212:213]
	v_lshl_add_u64 v[212:213], s[14:15], 0, v[212:213]
	global_load_dwordx4 v[132:135], v[212:213], off
	global_load_dwordx4 v[136:139], v[212:213], off offset:16
	global_load_dwordx4 v[140:143], v[212:213], off offset:32
	global_load_dwordx4 v[144:147], v[212:213], off offset:48
	global_load_dwordx4 v[174:177], v[212:213], off offset:1024
	global_load_dwordx4 v[178:181], v[212:213], off offset:1040
	global_load_dwordx4 v[182:185], v[212:213], off offset:1056
	global_load_dwordx4 v[186:189], v[212:213], off offset:1072
	v_and_b32_e32 v214, 15, v210
	v_lshlrev_b32_e32 v214, 2, v214
	v_add_u32_e32 v215, 64, v214
	v_add_u32_e32 v216, 0x80, v214
	v_add_u32_e32 v217, 0xc0, v214
	s_waitcnt vmcnt(4)
	v_add_f32_e32 v132, v132, v133
	v_add_f32_e32 v134, v134, v135
	v_add_f32_e32 v132, v132, v134
	v_add_f32_e32 v136, v136, v137
	v_add_f32_e32 v138, v138, v139
	v_add_f32_e32 v136, v136, v138
	v_add_f32_e32 v140, v140, v141
	v_add_f32_e32 v142, v142, v143
	v_add_f32_e32 v140, v140, v142
	v_add_f32_e32 v144, v144, v145
	v_add_f32_e32 v146, v146, v147
	v_add_f32_e32 v144, v144, v146
	v_add_f32_e32 v132, v132, v136
	v_add_f32_e32 v140, v140, v144
	v_add_f32_e32 v132, v132, v140
	v_fmamk_f32 v132, v132, 0x3a800000, v229
	v_cmp_gt_f32_e32 vcc, 0xf800000, v132
	v_mul_f32_e32 v137, 0x4f800000, v132
	s_nop 0
	v_cndmask_b32_e32 v132, v132, v137, vcc
	v_sqrt_f32_e32 v137, v132
	s_nop 0
	v_add_u32_e32 v138, -1, v137
	v_fma_f32 v139, -v138, v137, v132
	v_cmp_ge_f32_e64 s[100:101], 0, v139
	v_add_u32_e32 v139, 1, v137
	s_nop 0
	v_cndmask_b32_e64 v138, v137, v138, s[100:101]
	v_fma_f32 v137, -v139, v137, v132
	v_cmp_lt_f32_e64 s[100:101], 0, v137
	s_nop 1
	v_cndmask_b32_e64 v137, v138, v139, s[100:101]
	v_mul_f32_e32 v138, 0x37800000, v137
	v_cndmask_b32_e32 v137, v137, v138, vcc
	v_cmp_class_f32_e32 vcc, v132, v230
	s_nop 1
	v_cndmask_b32_e32 v132, v137, v132, vcc
	v_div_scale_f32 v137, s[100:101], v132, v132, 1.0
	v_rcp_f32_e32 v138, v137
	s_nop 0
	v_fma_f32 v139, -v137, v138, 1.0
	v_fmac_f32_e32 v138, v139, v138
	v_div_scale_f32 v139, vcc, 1.0, v132, 1.0
	v_mul_f32_e32 v141, v139, v138
	v_fma_f32 v142, -v137, v141, v139
	v_fmac_f32_e32 v141, v142, v138
	v_fma_f32 v137, -v137, v141, v139
	v_div_fmas_f32 v137, v137, v138, v141
	v_div_fixup_f32 v218, v137, v132, 1.0
	s_waitcnt vmcnt(0)
	v_add_f32_e32 v174, v174, v175
	v_add_f32_e32 v176, v176, v177
	v_add_f32_e32 v174, v174, v176
	v_add_f32_e32 v178, v178, v179
	v_add_f32_e32 v180, v180, v181
	v_add_f32_e32 v178, v178, v180
	v_add_f32_e32 v182, v182, v183
	v_add_f32_e32 v184, v184, v185
	v_add_f32_e32 v182, v182, v184
	v_add_f32_e32 v186, v186, v187
	v_add_f32_e32 v188, v188, v189
	v_add_f32_e32 v186, v186, v188
	v_add_f32_e32 v174, v174, v178
	v_add_f32_e32 v182, v182, v186
	v_add_f32_e32 v174, v174, v182
	v_fmamk_f32 v174, v174, 0x3a800000, v229
	v_cmp_gt_f32_e32 vcc, 0xf800000, v174
	v_mul_f32_e32 v179, 0x4f800000, v174
	s_nop 0
	v_cndmask_b32_e32 v174, v174, v179, vcc
	v_sqrt_f32_e32 v179, v174
	s_nop 0
	v_add_u32_e32 v180, -1, v179
	v_fma_f32 v181, -v180, v179, v174
	v_cmp_ge_f32_e64 s[100:101], 0, v181
	v_add_u32_e32 v181, 1, v179
	s_nop 0
	v_cndmask_b32_e64 v180, v179, v180, s[100:101]
	v_fma_f32 v179, -v181, v179, v174
	v_cmp_lt_f32_e64 s[100:101], 0, v179
	s_nop 1
	v_cndmask_b32_e64 v179, v180, v181, s[100:101]
	v_mul_f32_e32 v180, 0x37800000, v179
	v_cndmask_b32_e32 v179, v179, v180, vcc
	v_cmp_class_f32_e32 vcc, v174, v230
	s_nop 1
	v_cndmask_b32_e32 v174, v179, v174, vcc
	v_div_scale_f32 v179, s[100:101], v174, v174, 1.0
	v_rcp_f32_e32 v180, v179
	s_nop 0
	v_fma_f32 v181, -v179, v180, 1.0
	v_fmac_f32_e32 v180, v181, v180
	v_div_scale_f32 v181, vcc, 1.0, v174, 1.0
	v_mul_f32_e32 v183, v181, v180
	v_fma_f32 v184, -v179, v183, v181
	v_fmac_f32_e32 v183, v184, v180
	v_fma_f32 v179, -v179, v183, v181
	v_div_fmas_f32 v179, v179, v180, v183
	v_div_fixup_f32 v219, v179, v174, 1.0
	ds_bpermute_b32 v236, v214, v218
	ds_bpermute_b32 v237, v214, v219
	ds_bpermute_b32 v238, v215, v218
	ds_bpermute_b32 v239, v215, v219
	ds_bpermute_b32 v244, v216, v218
	ds_bpermute_b32 v245, v216, v219
	ds_bpermute_b32 v246, v217, v218
	ds_bpermute_b32 v247, v217, v219
	s_waitcnt lgkmcnt(0)
	v_mov_b32_e32 v241, s44

;     __device__ __forceinline__ void operator()(const pg8::f32x4 (&acc)[2][2][4][2], const pg8::Unit& u, int wr, int wc, int fr, int fq) const {
;     ...
;                         if (vt_all || (vt_half && bj == 1)) {
;                             bf16_t* vp = vt + (size_t)(vrow0 + bj * 128) * S + row;
;                             vp[0 * (size_t)S] = (bf16_t)(w.x & 0xffffu); vp[1 * (size_t)S] = (bf16_t)(w.x >> 16); vp[2 * (size_t)S] = (bf16_t)(w.y & 0xffffu); vp[3 * (size_t)S] = (bf16_t)(w.y >> 16);
;                             vp[4 * (size_t)S] = (bf16_t)(w.z & 0xffffu); vp[5 * (size_t)S] = (bf16_t)(w.z >> 16); vp[6 * (size_t)S] = (bf16_t)(w.w & 0xffffu); vp[7 * (size_t)S] = (bf16_t)(w.w >> 16);
.LBB0_354:
	v_or_b32_e32 v128, s21, v171
	s_andn2_b64 vcc, exec, s[4:5]
	v_ashrrev_i32_e32 v129, 31, v128
	s_cbranch_vccnz .LBB0_356
	ds_write_b128 v226, v[124:127]
	v_lshlrev_b64 v[130:131], 15, v[128:129]
	v_lshl_add_u64 v[130:131], s[6:7], 0, v[130:131]
	v_lshl_add_u64 v[130:131], v[250:251], 1, v[130:131]
	v_lshl_add_u64 v[130:131], v[248:249], 0, v[130:131]
	v_add_co_u32_e32 v140, vcc, 0x8000, v130
	s_waitcnt lgkmcnt(0)
	ds_read_b64_tr_b16 v[124:125], v227
	ds_read_b64_tr_b16 v[126:127], v227 offset:128
	s_waitcnt lgkmcnt(0)
	global_store_dwordx4 v[130:131], v[124:127], off
	s_nop 1

; __device__ __forceinline__ unsigned pk2(float lo, float hi) { return pg8::cvt_pk_bf16(lo, hi); }
;     __device__ __forceinline__ void operator()(const pg8::f32x4 (&acc)[2][2][4][2], const pg8::Unit& u, int wr, int wc, int fr, int fq) const {
;     ...
;                         const pg8::f32x4 v0 = acc[ai][bj][m][0] * rs, v1 = acc[ai][bj][m][1] * rs;
;                         u32x4 w; w.x = pk2(v0[0], v0[1]); w.y = pk2(v0[2], v0[3]); w.z = pk2(v1[0], v1[1]); w.w = pk2(v1[2], v1[3]);
;                         if (vt_all || (vt_half && bj == 1)) {
;                             bf16_t* vp = vt + (size_t)(vrow0 + bj * 128) * S + row;
;                             vp[0 * (size_t)S] = (bf16_t)(w.x & 0xffffu); vp[1 * (size_t)S] = (bf16_t)(w.x >> 16); vp[2 * (size_t)S] = (bf16_t)(w.y & 0xffffu); vp[3 * (size_t)S] = (bf16_t)(w.y >> 16);
;                             vp[4 * (size_t)S] = (bf16_t)(w.z & 0xffffu); vp[5 * (size_t)S] = (bf16_t)(w.z >> 16); vp[6 * (size_t)S] = (bf16_t)(w.w & 0xffffu); vp[7 * (size_t)S] = (bf16_t)(w.w >> 16);
.LBB0_363:
	s_and_b64 vcc, exec, s[0:1]
	s_cbranch_vccz .LBB0_365
	ds_write_b128 v226, v[116:119]
	v_lshlrev_b64 v[120:121], 15, v[128:129]
	v_lshl_add_u64 v[120:121], s[6:7], 0, v[120:121]
	v_lshl_add_u64 v[120:121], v[250:251], 1, v[120:121]
	v_lshl_add_u64 v[120:121], v[248:249], 0, v[120:121]
	v_add_co_u32_e32 v122, vcc, 0x400000, v120
	s_nop 1
	v_addc_co_u32_e32 v123, vcc, 0, v121, vcc
	s_waitcnt lgkmcnt(0)
	ds_read_b64_tr_b16 v[116:117], v227
	ds_read_b64_tr_b16 v[118:119], v227 offset:128
	s_waitcnt lgkmcnt(0)
	global_store_dwordx4 v[122:123], v[116:119], off
	s_nop 1

; __device__ __forceinline__ unsigned pk2(float lo, float hi) { return pg8::cvt_pk_bf16(lo, hi); }
;     __device__ __forceinline__ void operator()(const pg8::f32x4 (&acc)[2][2][4][2], const pg8::Unit& u, int wr, int wc, int fr, int fq) const {
;     ...
;                         const pg8::f32x4 v0 = acc[ai][bj][m][0] * rs, v1 = acc[ai][bj][m][1] * rs;
;                         u32x4 w; w.x = pk2(v0[0], v0[1]); w.y = pk2(v0[2], v0[3]); w.z = pk2(v1[0], v1[1]); w.w = pk2(v1[2], v1[3]);
;                         if (vt_all || (vt_half && bj == 1)) {
;                             bf16_t* vp = vt + (size_t)(vrow0 + bj * 128) * S + row;
;                             vp[0 * (size_t)S] = (bf16_t)(w.x & 0xffffu); vp[1 * (size_t)S] = (bf16_t)(w.x >> 16); vp[2 * (size_t)S] = (bf16_t)(w.y & 0xffffu); vp[3 * (size_t)S] = (bf16_t)(w.y >> 16);
;                             vp[4 * (size_t)S] = (bf16_t)(w.z & 0xffffu); vp[5 * (size_t)S] = (bf16_t)(w.z >> 16); vp[6 * (size_t)S] = (bf16_t)(w.w & 0xffffu); vp[7 * (size_t)S] = (bf16_t)(w.w >> 16);
.LBB0_374:
	ds_write_b128 v226, v[108:111]
	v_lshlrev_b64 v[112:113], 15, v[128:129]
	v_lshl_add_u64 v[112:113], s[6:7], 0, v[112:113]
	v_lshl_add_u64 v[112:113], v[250:251], 1, v[112:113]
	v_lshl_add_u64 v[112:113], v[248:249], 0, v[112:113]
	v_add_co_u32_e32 v114, vcc, 0x8000, v112
	s_waitcnt lgkmcnt(0)
	ds_read_b64_tr_b16 v[108:109], v227
	ds_read_b64_tr_b16 v[110:111], v227 offset:128
	s_waitcnt lgkmcnt(0)
	global_store_dwordx4 v[112:113], v[108:111], off offset:32
	s_nop 1
	v_mov_b32_e32 v119, v118
	s_cmp_lt_i32 s57, 10
	s_cbranch_scc0 .LBB0_372

; __device__ __forceinline__ unsigned pk2(float lo, float hi) { return pg8::cvt_pk_bf16(lo, hi); }
;     __device__ __forceinline__ void operator()(const pg8::f32x4 (&acc)[2][2][4][2], const pg8::Unit& u, int wr, int wc, int fr, int fq) const {
;     ...
;                         const pg8::f32x4 v0 = acc[ai][bj][m][0] * rs, v1 = acc[ai][bj][m][1] * rs;
;                         u32x4 w; w.x = pk2(v0[0], v0[1]); w.y = pk2(v0[2], v0[3]); w.z = pk2(v1[0], v1[1]); w.w = pk2(v1[2], v1[3]);
;                         if (vt_all || (vt_half && bj == 1)) {
;                             bf16_t* vp = vt + (size_t)(vrow0 + bj * 128) * S + row;
;                             vp[0 * (size_t)S] = (bf16_t)(w.x & 0xffffu); vp[1 * (size_t)S] = (bf16_t)(w.x >> 16); vp[2 * (size_t)S] = (bf16_t)(w.y & 0xffffu); vp[3 * (size_t)S] = (bf16_t)(w.y >> 16);
;                             vp[4 * (size_t)S] = (bf16_t)(w.z & 0xffffu); vp[5 * (size_t)S] = (bf16_t)(w.z >> 16); vp[6 * (size_t)S] = (bf16_t)(w.w & 0xffffu); vp[7 * (size_t)S] = (bf16_t)(w.w >> 16);
.LBB0_380:
	s_and_b64 vcc, exec, s[0:1]
	s_cbranch_vccz .LBB0_382
	ds_write_b128 v226, v[100:103]
	v_lshlrev_b64 v[104:105], 15, v[128:129]
	v_lshl_add_u64 v[104:105], s[6:7], 0, v[104:105]
	v_lshl_add_u64 v[104:105], v[250:251], 1, v[104:105]
	v_lshl_add_u64 v[104:105], v[248:249], 0, v[104:105]
	v_add_co_u32_e32 v106, vcc, 0x400000, v104
	s_nop 1
	v_addc_co_u32_e32 v107, vcc, 0, v105, vcc
	s_waitcnt lgkmcnt(0)
	ds_read_b64_tr_b16 v[100:101], v227
	ds_read_b64_tr_b16 v[102:103], v227 offset:128
	s_waitcnt lgkmcnt(0)
	global_store_dwordx4 v[106:107], v[100:103], off offset:32
	s_nop 1

; __device__ __forceinline__ unsigned pk2(float lo, float hi) { return pg8::cvt_pk_bf16(lo, hi); }
;     __device__ __forceinline__ void operator()(const pg8::f32x4 (&acc)[2][2][4][2], const pg8::Unit& u, int wr, int wc, int fr, int fq) const {
;     ...
;                         const pg8::f32x4 v0 = acc[ai][bj][m][0] * rs, v1 = acc[ai][bj][m][1] * rs;
;                         u32x4 w; w.x = pk2(v0[0], v0[1]); w.y = pk2(v0[2], v0[3]); w.z = pk2(v1[0], v1[1]); w.w = pk2(v1[2], v1[3]);
;                         if (vt_all || (vt_half && bj == 1)) {
;                             bf16_t* vp = vt + (size_t)(vrow0 + bj * 128) * S + row;
;                             vp[0 * (size_t)S] = (bf16_t)(w.x & 0xffffu); vp[1 * (size_t)S] = (bf16_t)(w.x >> 16); vp[2 * (size_t)S] = (bf16_t)(w.y & 0xffffu); vp[3 * (size_t)S] = (bf16_t)(w.y >> 16);
;                             vp[4 * (size_t)S] = (bf16_t)(w.z & 0xffffu); vp[5 * (size_t)S] = (bf16_t)(w.z >> 16); vp[6 * (size_t)S] = (bf16_t)(w.w & 0xffffu); vp[7 * (size_t)S] = (bf16_t)(w.w >> 16);
.LBB0_391:
	ds_write_b128 v226, v[92:95]
	v_lshlrev_b64 v[96:97], 15, v[128:129]
	v_lshl_add_u64 v[96:97], s[6:7], 0, v[96:97]
	v_lshl_add_u64 v[96:97], v[250:251], 1, v[96:97]
	v_lshl_add_u64 v[96:97], v[248:249], 0, v[96:97]
	v_add_co_u32_e32 v98, vcc, 0x8000, v96
	s_waitcnt lgkmcnt(0)
	ds_read_b64_tr_b16 v[92:93], v227
	ds_read_b64_tr_b16 v[94:95], v227 offset:128
	s_waitcnt lgkmcnt(0)
	global_store_dwordx4 v[96:97], v[92:95], off offset:64
	s_nop 1
	v_mov_b32_e32 v103, v102
	s_cmp_lt_i32 s57, 10
	s_cbranch_scc0 .LBB0_389

; __device__ __forceinline__ unsigned pk2(float lo, float hi) { return pg8::cvt_pk_bf16(lo, hi); }
;     __device__ __forceinline__ void operator()(const pg8::f32x4 (&acc)[2][2][4][2], const pg8::Unit& u, int wr, int wc, int fr, int fq) const {
;     ...
;                         const pg8::f32x4 v0 = acc[ai][bj][m][0] * rs, v1 = acc[ai][bj][m][1] * rs;
;                         u32x4 w; w.x = pk2(v0[0], v0[1]); w.y = pk2(v0[2], v0[3]); w.z = pk2(v1[0], v1[1]); w.w = pk2(v1[2], v1[3]);
;                         if (vt_all || (vt_half && bj == 1)) {
;                             bf16_t* vp = vt + (size_t)(vrow0 + bj * 128) * S + row;
;                             vp[0 * (size_t)S] = (bf16_t)(w.x & 0xffffu); vp[1 * (size_t)S] = (bf16_t)(w.x >> 16); vp[2 * (size_t)S] = (bf16_t)(w.y & 0xffffu); vp[3 * (size_t)S] = (bf16_t)(w.y >> 16);
;                             vp[4 * (size_t)S] = (bf16_t)(w.z & 0xffffu); vp[5 * (size_t)S] = (bf16_t)(w.z >> 16); vp[6 * (size_t)S] = (bf16_t)(w.w & 0xffffu); vp[7 * (size_t)S] = (bf16_t)(w.w >> 16);
.LBB0_397:
	s_and_b64 vcc, exec, s[0:1]
	s_cbranch_vccz .LBB0_399
	ds_write_b128 v226, v[84:87]
	v_lshlrev_b64 v[88:89], 15, v[128:129]
	v_lshl_add_u64 v[88:89], s[6:7], 0, v[88:89]
	v_lshl_add_u64 v[88:89], v[250:251], 1, v[88:89]
	v_lshl_add_u64 v[88:89], v[248:249], 0, v[88:89]
	v_add_co_u32_e32 v90, vcc, 0x400000, v88
	s_nop 1
	v_addc_co_u32_e32 v91, vcc, 0, v89, vcc
	s_waitcnt lgkmcnt(0)
	ds_read_b64_tr_b16 v[84:85], v227
	ds_read_b64_tr_b16 v[86:87], v227 offset:128
	s_waitcnt lgkmcnt(0)
	global_store_dwordx4 v[90:91], v[84:87], off offset:64
	s_nop 1

; __device__ __forceinline__ unsigned pk2(float lo, float hi) { return pg8::cvt_pk_bf16(lo, hi); }
;     __device__ __forceinline__ void operator()(const pg8::f32x4 (&acc)[2][2][4][2], const pg8::Unit& u, int wr, int wc, int fr, int fq) const {
;     ...
;                         const pg8::f32x4 v0 = acc[ai][bj][m][0] * rs, v1 = acc[ai][bj][m][1] * rs;
;                         u32x4 w; w.x = pk2(v0[0], v0[1]); w.y = pk2(v0[2], v0[3]); w.z = pk2(v1[0], v1[1]); w.w = pk2(v1[2], v1[3]);
;                         if (vt_all || (vt_half && bj == 1)) {
;                             bf16_t* vp = vt + (size_t)(vrow0 + bj * 128) * S + row;
;                             vp[0 * (size_t)S] = (bf16_t)(w.x & 0xffffu); vp[1 * (size_t)S] = (bf16_t)(w.x >> 16); vp[2 * (size_t)S] = (bf16_t)(w.y & 0xffffu); vp[3 * (size_t)S] = (bf16_t)(w.y >> 16);
;                             vp[4 * (size_t)S] = (bf16_t)(w.z & 0xffffu); vp[5 * (size_t)S] = (bf16_t)(w.z >> 16); vp[6 * (size_t)S] = (bf16_t)(w.w & 0xffffu); vp[7 * (size_t)S] = (bf16_t)(w.w >> 16);
.LBB0_408:
	ds_write_b128 v226, v[76:79]
	v_lshlrev_b64 v[80:81], 15, v[128:129]
	v_lshl_add_u64 v[80:81], s[6:7], 0, v[80:81]
	v_lshl_add_u64 v[80:81], v[250:251], 1, v[80:81]
	v_lshl_add_u64 v[80:81], v[248:249], 0, v[80:81]
	v_add_co_u32_e32 v82, vcc, 0x8000, v80
	s_waitcnt lgkmcnt(0)
	ds_read_b64_tr_b16 v[76:77], v227
	ds_read_b64_tr_b16 v[78:79], v227 offset:128
	s_waitcnt lgkmcnt(0)
	global_store_dwordx4 v[80:81], v[76:79], off offset:96
	s_nop 1
	v_mov_b32_e32 v87, v86
	s_cmp_lt_i32 s57, 10
	s_cbranch_scc0 .LBB0_406

; __device__ __forceinline__ unsigned pk2(float lo, float hi) { return pg8::cvt_pk_bf16(lo, hi); }
;     __device__ __forceinline__ void operator()(const pg8::f32x4 (&acc)[2][2][4][2], const pg8::Unit& u, int wr, int wc, int fr, int fq) const {
;     ...
;                         const pg8::f32x4 v0 = acc[ai][bj][m][0] * rs, v1 = acc[ai][bj][m][1] * rs;
;                         u32x4 w; w.x = pk2(v0[0], v0[1]); w.y = pk2(v0[2], v0[3]); w.z = pk2(v1[0], v1[1]); w.w = pk2(v1[2], v1[3]);
;                         if (vt_all || (vt_half && bj == 1)) {
;                             bf16_t* vp = vt + (size_t)(vrow0 + bj * 128) * S + row;
;                             vp[0 * (size_t)S] = (bf16_t)(w.x & 0xffffu); vp[1 * (size_t)S] = (bf16_t)(w.x >> 16); vp[2 * (size_t)S] = (bf16_t)(w.y & 0xffffu); vp[3 * (size_t)S] = (bf16_t)(w.y >> 16);
;                             vp[4 * (size_t)S] = (bf16_t)(w.z & 0xffffu); vp[5 * (size_t)S] = (bf16_t)(w.z >> 16); vp[6 * (size_t)S] = (bf16_t)(w.w & 0xffffu); vp[7 * (size_t)S] = (bf16_t)(w.w >> 16);
.LBB0_414:
	s_and_b64 vcc, exec, s[0:1]
	s_cbranch_vccz .LBB0_416
	ds_write_b128 v226, v[68:71]
	v_lshlrev_b64 v[72:73], 15, v[128:129]
	v_lshl_add_u64 v[72:73], s[6:7], 0, v[72:73]
	v_lshl_add_u64 v[72:73], v[250:251], 1, v[72:73]
	v_lshl_add_u64 v[72:73], v[248:249], 0, v[72:73]
	v_add_co_u32_e32 v74, vcc, 0x400000, v72
	s_nop 1
	v_addc_co_u32_e32 v75, vcc, 0, v73, vcc
	s_waitcnt lgkmcnt(0)
	ds_read_b64_tr_b16 v[68:69], v227
	ds_read_b64_tr_b16 v[70:71], v227 offset:128
	s_waitcnt lgkmcnt(0)
	global_store_dwordx4 v[74:75], v[68:71], off offset:96
	s_nop 1

; __device__ __forceinline__ unsigned pk2(float lo, float hi) { return pg8::cvt_pk_bf16(lo, hi); }
;     __device__ __forceinline__ void operator()(const pg8::f32x4 (&acc)[2][2][4][2], const pg8::Unit& u, int wr, int wc, int fr, int fq) const {
;     ...
;                         const pg8::f32x4 v0 = acc[ai][bj][m][0] * rs, v1 = acc[ai][bj][m][1] * rs;
;                         u32x4 w; w.x = pk2(v0[0], v0[1]); w.y = pk2(v0[2], v0[3]); w.z = pk2(v1[0], v1[1]); w.w = pk2(v1[2], v1[3]);
;                         if (vt_all || (vt_half && bj == 1)) {
;                             bf16_t* vp = vt + (size_t)(vrow0 + bj * 128) * S + row;
;                             vp[0 * (size_t)S] = (bf16_t)(w.x & 0xffffu); vp[1 * (size_t)S] = (bf16_t)(w.x >> 16); vp[2 * (size_t)S] = (bf16_t)(w.y & 0xffffu); vp[3 * (size_t)S] = (bf16_t)(w.y >> 16);
;                             vp[4 * (size_t)S] = (bf16_t)(w.z & 0xffffu); vp[5 * (size_t)S] = (bf16_t)(w.z >> 16); vp[6 * (size_t)S] = (bf16_t)(w.w & 0xffffu); vp[7 * (size_t)S] = (bf16_t)(w.w >> 16);
.LBB0_425:
	ds_write_b128 v226, v[60:63]
	v_lshlrev_b64 v[64:65], 15, v[128:129]
	v_lshl_add_u64 v[64:65], s[6:7], 0, v[64:65]
	v_lshl_add_u64 v[64:65], v[250:251], 1, v[64:65]
	v_lshl_add_u64 v[64:65], v[248:249], 0, v[64:65]
	v_add_co_u32_e32 v66, vcc, 0x8000, v64
	s_waitcnt lgkmcnt(0)
	ds_read_b64_tr_b16 v[60:61], v227
	ds_read_b64_tr_b16 v[62:63], v227 offset:128
	s_waitcnt lgkmcnt(0)
	global_store_dwordx4 v[64:65], v[60:63], off offset:256
	s_nop 1
	v_mov_b32_e32 v71, v70
	s_cmp_lt_i32 s57, 10
	s_cbranch_scc0 .LBB0_423

; __device__ __forceinline__ unsigned pk2(float lo, float hi) { return pg8::cvt_pk_bf16(lo, hi); }
;     __device__ __forceinline__ void operator()(const pg8::f32x4 (&acc)[2][2][4][2], const pg8::Unit& u, int wr, int wc, int fr, int fq) const {
;     ...
;                         const pg8::f32x4 v0 = acc[ai][bj][m][0] * rs, v1 = acc[ai][bj][m][1] * rs;
;                         u32x4 w; w.x = pk2(v0[0], v0[1]); w.y = pk2(v0[2], v0[3]); w.z = pk2(v1[0], v1[1]); w.w = pk2(v1[2], v1[3]);
;                         if (vt_all || (vt_half && bj == 1)) {
;                             bf16_t* vp = vt + (size_t)(vrow0 + bj * 128) * S + row;
;                             vp[0 * (size_t)S] = (bf16_t)(w.x & 0xffffu); vp[1 * (size_t)S] = (bf16_t)(w.x >> 16); vp[2 * (size_t)S] = (bf16_t)(w.y & 0xffffu); vp[3 * (size_t)S] = (bf16_t)(w.y >> 16);
;                             vp[4 * (size_t)S] = (bf16_t)(w.z & 0xffffu); vp[5 * (size_t)S] = (bf16_t)(w.z >> 16); vp[6 * (size_t)S] = (bf16_t)(w.w & 0xffffu); vp[7 * (size_t)S] = (bf16_t)(w.w >> 16);
.LBB0_431:
	s_and_b64 vcc, exec, s[0:1]
	s_cbranch_vccz .LBB0_433
	ds_write_b128 v226, v[52:55]
	v_lshlrev_b64 v[56:57], 15, v[128:129]
	v_lshl_add_u64 v[56:57], s[6:7], 0, v[56:57]
	v_lshl_add_u64 v[56:57], v[250:251], 1, v[56:57]
	v_lshl_add_u64 v[56:57], v[248:249], 0, v[56:57]
	v_add_co_u32_e32 v58, vcc, 0x400000, v56
	s_nop 1
	v_addc_co_u32_e32 v59, vcc, 0, v57, vcc
	s_waitcnt lgkmcnt(0)
	ds_read_b64_tr_b16 v[52:53], v227
	ds_read_b64_tr_b16 v[54:55], v227 offset:128
	s_waitcnt lgkmcnt(0)
	global_store_dwordx4 v[58:59], v[52:55], off offset:256
	s_nop 1

; __device__ __forceinline__ unsigned pk2(float lo, float hi) { return pg8::cvt_pk_bf16(lo, hi); }
;     __device__ __forceinline__ void operator()(const pg8::f32x4 (&acc)[2][2][4][2], const pg8::Unit& u, int wr, int wc, int fr, int fq) const {
;     ...
;                         const pg8::f32x4 v0 = acc[ai][bj][m][0] * rs, v1 = acc[ai][bj][m][1] * rs;
;                         u32x4 w; w.x = pk2(v0[0], v0[1]); w.y = pk2(v0[2], v0[3]); w.z = pk2(v1[0], v1[1]); w.w = pk2(v1[2], v1[3]);
;                         if (vt_all || (vt_half && bj == 1)) {
;                             bf16_t* vp = vt + (size_t)(vrow0 + bj * 128) * S + row;
;                             vp[0 * (size_t)S] = (bf16_t)(w.x & 0xffffu); vp[1 * (size_t)S] = (bf16_t)(w.x >> 16); vp[2 * (size_t)S] = (bf16_t)(w.y & 0xffffu); vp[3 * (size_t)S] = (bf16_t)(w.y >> 16);
;                             vp[4 * (size_t)S] = (bf16_t)(w.z & 0xffffu); vp[5 * (size_t)S] = (bf16_t)(w.z >> 16); vp[6 * (size_t)S] = (bf16_t)(w.w & 0xffffu); vp[7 * (size_t)S] = (bf16_t)(w.w >> 16);
.LBB0_442:
	ds_write_b128 v226, v[44:47]
	v_lshlrev_b64 v[48:49], 15, v[128:129]
	v_lshl_add_u64 v[48:49], s[6:7], 0, v[48:49]
	v_lshl_add_u64 v[48:49], v[250:251], 1, v[48:49]
	v_lshl_add_u64 v[48:49], v[248:249], 0, v[48:49]
	v_add_co_u32_e32 v50, vcc, 0x8000, v48
	s_waitcnt lgkmcnt(0)
	ds_read_b64_tr_b16 v[44:45], v227
	ds_read_b64_tr_b16 v[46:47], v227 offset:128
	s_waitcnt lgkmcnt(0)
	global_store_dwordx4 v[48:49], v[44:47], off offset:288
	s_nop 1
	v_mov_b32_e32 v55, v54
	s_cmp_lt_i32 s57, 10
	s_cbranch_scc0 .LBB0_440

; __device__ __forceinline__ unsigned pk2(float lo, float hi) { return pg8::cvt_pk_bf16(lo, hi); }
;     __device__ __forceinline__ void operator()(const pg8::f32x4 (&acc)[2][2][4][2], const pg8::Unit& u, int wr, int wc, int fr, int fq) const {
;     ...
;                         const pg8::f32x4 v0 = acc[ai][bj][m][0] * rs, v1 = acc[ai][bj][m][1] * rs;
;                         u32x4 w; w.x = pk2(v0[0], v0[1]); w.y = pk2(v0[2], v0[3]); w.z = pk2(v1[0], v1[1]); w.w = pk2(v1[2], v1[3]);
;                         if (vt_all || (vt_half && bj == 1)) {
;                             bf16_t* vp = vt + (size_t)(vrow0 + bj * 128) * S + row;
;                             vp[0 * (size_t)S] = (bf16_t)(w.x & 0xffffu); vp[1 * (size_t)S] = (bf16_t)(w.x >> 16); vp[2 * (size_t)S] = (bf16_t)(w.y & 0xffffu); vp[3 * (size_t)S] = (bf16_t)(w.y >> 16);
;                             vp[4 * (size_t)S] = (bf16_t)(w.z & 0xffffu); vp[5 * (size_t)S] = (bf16_t)(w.z >> 16); vp[6 * (size_t)S] = (bf16_t)(w.w & 0xffffu); vp[7 * (size_t)S] = (bf16_t)(w.w >> 16);
.LBB0_448:
	s_and_b64 vcc, exec, s[0:1]
	s_cbranch_vccz .LBB0_450
	ds_write_b128 v226, v[36:39]
	v_lshlrev_b64 v[40:41], 15, v[128:129]
	v_lshl_add_u64 v[40:41], s[6:7], 0, v[40:41]
	v_lshl_add_u64 v[40:41], v[250:251], 1, v[40:41]
	v_lshl_add_u64 v[40:41], v[248:249], 0, v[40:41]
	v_add_co_u32_e32 v42, vcc, 0x400000, v40
	s_nop 1
	v_addc_co_u32_e32 v43, vcc, 0, v41, vcc
	s_waitcnt lgkmcnt(0)
	ds_read_b64_tr_b16 v[36:37], v227
	ds_read_b64_tr_b16 v[38:39], v227 offset:128
	s_waitcnt lgkmcnt(0)
	global_store_dwordx4 v[42:43], v[36:39], off offset:288
	s_nop 1

; __device__ __forceinline__ unsigned pk2(float lo, float hi) { return pg8::cvt_pk_bf16(lo, hi); }
;     __device__ __forceinline__ void operator()(const pg8::f32x4 (&acc)[2][2][4][2], const pg8::Unit& u, int wr, int wc, int fr, int fq) const {
;     ...
;                         const pg8::f32x4 v0 = acc[ai][bj][m][0] * rs, v1 = acc[ai][bj][m][1] * rs;
;                         u32x4 w; w.x = pk2(v0[0], v0[1]); w.y = pk2(v0[2], v0[3]); w.z = pk2(v1[0], v1[1]); w.w = pk2(v1[2], v1[3]);
;                         if (vt_all || (vt_half && bj == 1)) {
;                             bf16_t* vp = vt + (size_t)(vrow0 + bj * 128) * S + row;
;                             vp[0 * (size_t)S] = (bf16_t)(w.x & 0xffffu); vp[1 * (size_t)S] = (bf16_t)(w.x >> 16); vp[2 * (size_t)S] = (bf16_t)(w.y & 0xffffu); vp[3 * (size_t)S] = (bf16_t)(w.y >> 16);
;                             vp[4 * (size_t)S] = (bf16_t)(w.z & 0xffffu); vp[5 * (size_t)S] = (bf16_t)(w.z >> 16); vp[6 * (size_t)S] = (bf16_t)(w.w & 0xffffu); vp[7 * (size_t)S] = (bf16_t)(w.w >> 16);
.LBB0_459:
	ds_write_b128 v226, v[24:27]
	v_lshlrev_b64 v[28:29], 15, v[128:129]
	v_lshl_add_u64 v[28:29], s[6:7], 0, v[28:29]
	v_lshl_add_u64 v[28:29], v[250:251], 1, v[28:29]
	v_lshl_add_u64 v[28:29], v[248:249], 0, v[28:29]
	v_add_co_u32_e32 v30, vcc, 0x8000, v28
	s_waitcnt lgkmcnt(0)
	ds_read_b64_tr_b16 v[24:25], v227
	ds_read_b64_tr_b16 v[26:27], v227 offset:128
	s_waitcnt lgkmcnt(0)
	global_store_dwordx4 v[28:29], v[24:27], off offset:320
	s_nop 1
	v_mov_b32_e32 v39, v38
	s_cmp_lt_i32 s57, 10
	s_cbranch_scc0 .LBB0_457

; __device__ __forceinline__ unsigned pk2(float lo, float hi) { return pg8::cvt_pk_bf16(lo, hi); }
;     __device__ __forceinline__ void operator()(const pg8::f32x4 (&acc)[2][2][4][2], const pg8::Unit& u, int wr, int wc, int fr, int fq) const {
;     ...
;                         const pg8::f32x4 v0 = acc[ai][bj][m][0] * rs, v1 = acc[ai][bj][m][1] * rs;
;                         u32x4 w; w.x = pk2(v0[0], v0[1]); w.y = pk2(v0[2], v0[3]); w.z = pk2(v1[0], v1[1]); w.w = pk2(v1[2], v1[3]);
;                         if (vt_all || (vt_half && bj == 1)) {
;                             bf16_t* vp = vt + (size_t)(vrow0 + bj * 128) * S + row;
;                             vp[0 * (size_t)S] = (bf16_t)(w.x & 0xffffu); vp[1 * (size_t)S] = (bf16_t)(w.x >> 16); vp[2 * (size_t)S] = (bf16_t)(w.y & 0xffffu); vp[3 * (size_t)S] = (bf16_t)(w.y >> 16);
;                             vp[4 * (size_t)S] = (bf16_t)(w.z & 0xffffu); vp[5 * (size_t)S] = (bf16_t)(w.z >> 16); vp[6 * (size_t)S] = (bf16_t)(w.w & 0xffffu); vp[7 * (size_t)S] = (bf16_t)(w.w >> 16);
.LBB0_465:
	s_and_b64 vcc, exec, s[0:1]
	s_cbranch_vccz .LBB0_467
	ds_write_b128 v226, v[16:19]
	v_lshlrev_b64 v[20:21], 15, v[128:129]
	v_lshl_add_u64 v[20:21], s[6:7], 0, v[20:21]
	v_lshl_add_u64 v[20:21], v[250:251], 1, v[20:21]
	v_lshl_add_u64 v[20:21], v[248:249], 0, v[20:21]
	v_add_co_u32_e32 v22, vcc, 0x400000, v20
	s_nop 1
	v_addc_co_u32_e32 v23, vcc, 0, v21, vcc
	s_waitcnt lgkmcnt(0)
	ds_read_b64_tr_b16 v[16:17], v227
	ds_read_b64_tr_b16 v[18:19], v227 offset:128
	s_waitcnt lgkmcnt(0)
	global_store_dwordx4 v[22:23], v[16:19], off offset:320
	s_nop 1

; __device__ __forceinline__ unsigned pk2(float lo, float hi) { return pg8::cvt_pk_bf16(lo, hi); }
;     __device__ __forceinline__ void operator()(const pg8::f32x4 (&acc)[2][2][4][2], const pg8::Unit& u, int wr, int wc, int fr, int fq) const {
;     ...
;                         const pg8::f32x4 v0 = acc[ai][bj][m][0] * rs, v1 = acc[ai][bj][m][1] * rs;
;                         u32x4 w; w.x = pk2(v0[0], v0[1]); w.y = pk2(v0[2], v0[3]); w.z = pk2(v1[0], v1[1]); w.w = pk2(v1[2], v1[3]);
;                         if (vt_all || (vt_half && bj == 1)) {
;                             bf16_t* vp = vt + (size_t)(vrow0 + bj * 128) * S + row;
;                             vp[0 * (size_t)S] = (bf16_t)(w.x & 0xffffu); vp[1 * (size_t)S] = (bf16_t)(w.x >> 16); vp[2 * (size_t)S] = (bf16_t)(w.y & 0xffffu); vp[3 * (size_t)S] = (bf16_t)(w.y >> 16);
;                             vp[4 * (size_t)S] = (bf16_t)(w.z & 0xffffu); vp[5 * (size_t)S] = (bf16_t)(w.z >> 16); vp[6 * (size_t)S] = (bf16_t)(w.w & 0xffffu); vp[7 * (size_t)S] = (bf16_t)(w.w >> 16);
.LBB0_476:
	ds_write_b128 v226, v[8:11]
	v_lshlrev_b64 v[12:13], 15, v[128:129]
	v_lshl_add_u64 v[12:13], s[6:7], 0, v[12:13]
	v_lshl_add_u64 v[12:13], v[250:251], 1, v[12:13]
	v_lshl_add_u64 v[12:13], v[248:249], 0, v[12:13]
	v_add_co_u32_e32 v14, vcc, 0x8000, v12
	s_waitcnt lgkmcnt(0)
	ds_read_b64_tr_b16 v[8:9], v227
	ds_read_b64_tr_b16 v[10:11], v227 offset:128
	s_waitcnt lgkmcnt(0)
	global_store_dwordx4 v[12:13], v[8:11], off offset:352
	s_nop 1
	v_mov_b32_e32 v19, v18
	s_cmp_lt_i32 s57, 10
	s_cbranch_scc0 .LBB0_474

; __device__ __forceinline__ unsigned pk2(float lo, float hi) { return pg8::cvt_pk_bf16(lo, hi); }
;     __device__ __forceinline__ void operator()(const pg8::f32x4 (&acc)[2][2][4][2], const pg8::Unit& u, int wr, int wc, int fr, int fq) const {
;     ...
;                         const pg8::f32x4 v0 = acc[ai][bj][m][0] * rs, v1 = acc[ai][bj][m][1] * rs;
;                         u32x4 w; w.x = pk2(v0[0], v0[1]); w.y = pk2(v0[2], v0[3]); w.z = pk2(v1[0], v1[1]); w.w = pk2(v1[2], v1[3]);
;                         if (vt_all || (vt_half && bj == 1)) {
;                             bf16_t* vp = vt + (size_t)(vrow0 + bj * 128) * S + row;
;                             vp[0 * (size_t)S] = (bf16_t)(w.x & 0xffffu); vp[1 * (size_t)S] = (bf16_t)(w.x >> 16); vp[2 * (size_t)S] = (bf16_t)(w.y & 0xffffu); vp[3 * (size_t)S] = (bf16_t)(w.y >> 16);
;                             vp[4 * (size_t)S] = (bf16_t)(w.z & 0xffffu); vp[5 * (size_t)S] = (bf16_t)(w.z >> 16); vp[6 * (size_t)S] = (bf16_t)(w.w & 0xffffu); vp[7 * (size_t)S] = (bf16_t)(w.w >> 16);
.LBB0_483:
	s_and_b64 vcc, exec, s[0:1]
	s_cbranch_vccz .LBB0_485
	ds_write_b128 v226, v[0:3]
	v_lshlrev_b64 v[4:5], 15, v[128:129]
	v_lshl_add_u64 v[4:5], s[6:7], 0, v[4:5]
	v_lshl_add_u64 v[4:5], v[250:251], 1, v[4:5]
	v_lshl_add_u64 v[4:5], v[248:249], 0, v[4:5]
	v_add_co_u32_e32 v6, vcc, 0x400000, v4
	s_nop 1
	v_addc_co_u32_e32 v7, vcc, 0, v5, vcc
	s_waitcnt lgkmcnt(0)
	ds_read_b64_tr_b16 v[0:1], v227
	ds_read_b64_tr_b16 v[2:3], v227 offset:128
	s_waitcnt lgkmcnt(0)
	global_store_dwordx4 v[6:7], v[0:3], off offset:352
	s_nop 1
